# LB2: LB1 plus a runtime guard - XCD-local barriers after phases 16-18 only when every workgroup reports XCC id == bx&7 (flag in the zeroed control area, read once at the phase-15 barrier)
# baseline (speedup 1.0000x reference)
; #define LAS __attribute__((address_space(3)))
; __device__ __forceinline__ unsigned xb_add(unsigned* p, unsigned v) { return __hip_atomic_fetch_add(p, v, __ATOMIC_RELAXED, __HIP_MEMORY_SCOPE_AGENT); }
; __device__ __forceinline__ unsigned xb_xcc_id() { return (unsigned)__builtin_amdgcn_s_getreg((3 << 11) | 20) & 0xFu; }
; __device__ __forceinline__ XcdBarrier xcd_barrier_post(unsigned* bar, volatile LAS unsigned* st) {
;     XcdBarrier b; b.bar = bar; b.x = xb_xcc_id(); b.st = st;
;     if (threadIdx.x == 0) (void)xb_add(&bar[XB_XCNT(b.x)], 1u);
;     return b;
; }
; __device__ __forceinline__ void xcd_barrier(const XcdBarrier& b) {
;     asm volatile("s_waitcnt vmcnt(0)" ::: "memory");
;     __syncthreads();
;     if (threadIdx.x == 0) {
;         unsigned* bar = b.bar;
;         __builtin_amdgcn_s_waitcnt(0);
;         unsigned nloc = b.st[0], nx = b.st[1];
;         if (nloc == 0u) { xcd_barrier_complete(bar, b.x, nloc, nx); b.st[0] = nloc; b.st[1] = nx; }
;         const unsigned old = xb_add(&bar[XB_XSUB(b.x)], 1u);
.LBB0_1246:
	v_readlane_b32 s4, v243, 16
	s_cmp_lg_u32 s4, 0
	s_cbranch_scc1 .Lxg_n0
	v_readlane_b32 s4, v243, 19
	s_and_b32 s4, s4, 7
	s_cmp_eq_u32 s4, s44
	s_cbranch_scc1 .Lxg_n0
	s_add_u32 s4, s80, 0xf000
	s_addc_u32 s5, s81, 0
	v_mov_b32_e32 v242, 1
	global_store_dword v1, v242, s[4:5]
	s_waitcnt vmcnt(0)
.Lxg_n0:
	v_readlane_b32 s4, v243, 16
	s_cmp_lg_u32 s4, 15
	s_cbranch_scc1 .Lxg_n15
	s_add_u32 s4, s80, 0xf000
	s_addc_u32 s5, s81, 0
	global_load_dword v242, v1, s[4:5] sc1
	s_waitcnt vmcnt(0)
	v_readfirstlane_b32 s32, v242

; __device__ __forceinline__ unsigned xb_add(unsigned* p, unsigned v) { return __hip_atomic_fetch_add(p, v, __ATOMIC_RELAXED, __HIP_MEMORY_SCOPE_AGENT); }
; __device__ __forceinline__ void xcd_barrier(const XcdBarrier& b) {
;     ...
;     if (threadIdx.x == 0) {
;         unsigned* bar = b.bar;
;         __builtin_amdgcn_s_waitcnt(0);
;         unsigned nloc = b.st[0], nx = b.st[1];
;         if (nloc == 0u) { xcd_barrier_complete(bar, b.x, nloc, nx); b.st[0] = nloc; b.st[1] = nx; }
;         const unsigned old = xb_add(&bar[XB_XSUB(b.x)], 1u);
;         const unsigned gen = old / nloc;
;         if (old + 1u == (gen + 1u) * nloc) {
.LBB0_1263:
	v_readlane_b32 s4, v243, 16
	s_sub_i32 s4, s4, 16
	s_cmp_lt_u32 s4, 3
	s_cbranch_scc0 .Lbar_full
	s_cmp_eq_u32 s32, 0
	s_cbranch_scc1 .Lbar_local
